# SSD segment state hand-off: one release write-back per block (thread 0 after the workgroup barrier) instead of one per wave before it
# speedup vs baseline: 1.0396x; 1.0396x over previous
; template <int PROBE>
; PH void ssd_prompt_item(const Params& p, int layer, int b, int e, int seg) {
;     ...
;   if (seg < NSEG - 1) {
;     __builtin_amdgcn_fence(__ATOMIC_RELEASE, "agent");
;     asm volatile("s_waitcnt vmcnt(0)" ::: "memory");
;     __syncthreads();
;     if (tid == 0) __hip_atomic_store(SFLAG + seg, 1u, __ATOMIC_RELAXED, __HIP_MEMORY_SCOPE_AGENT);
;   }
.LBB0_558:
	s_and_b64 vcc, exec, s[0:1]
	s_cbranch_vccz .LBB0_609
	s_nop 0
	s_nop 0
	s_waitcnt vmcnt(0)
	s_waitcnt vmcnt(0)
	v_cmp_eq_u32_e32 vcc, 0, v174
	s_barrier
	s_and_saveexec_b64 s[0:1], vcc
	s_cbranch_execz .LBB0_561
	s_ashr_i32 s87, s86, 31
	s_lshl_b64 s[6:7], s[86:87], 2
	s_add_u32 s6, s18, s6
	s_addc_u32 s7, s23, s7
	buffer_wbl2 sc1
	s_waitcnt vmcnt(0)
	global_store_dword v161, v183, s[6:7] sc1
	s_nop 0
	s_nop 0
	s_nop 0
	s_nop 0
	s_nop 0
	s_nop 0
	s_nop 0
	s_nop 0
	s_nop 0
	s_nop 0
	s_nop 0
	s_nop 0
	s_nop 0
	s_nop 0
	s_nop 0
	s_nop 0
	s_nop 0
	s_nop 0
	s_nop 0
	s_nop 0
	s_nop 0
	s_nop 0
	s_nop 0
	s_nop 0
	s_nop 0
	s_nop 0
	s_nop 0
	s_nop 0
	s_nop 0
	s_nop 0
	s_nop 0
	s_nop 0
	s_nop 0
	s_nop 0
	s_nop 0
	s_nop 0
	s_nop 0
	s_nop 0
	s_nop 0
	s_nop 0
	s_nop 0
	s_nop 0
	s_nop 0
	s_nop 0
	s_nop 0
	s_nop 0
	s_nop 0
	s_nop 0
	s_nop 0
	s_nop 0
	s_nop 0
	s_nop 0
	s_nop 0
	s_nop 0
	s_nop 0
	s_nop 0
	s_nop 0
	s_nop 0
	s_nop 0
	s_nop 0
	s_nop 0
